# v022
# baseline (speedup 1.0000x reference)
; #define MFMA(a, b, c) __builtin_amdgcn_mfma_f32_16x16x32_bf16((a), (b), (c), 0, 0, 0)
; template <int EPI, int MF>
; __device__ __forceinline__ void gemm_part(const u16* __restrict__ A, int lda, const u16* __restrict__ Bt, int K, int ntn, GemmEpi ep, char* smem,
;                                           int mbase, int mrows) {
;     ...
;     GEMM_ISSUE(0);
;     GEMM_ISSUE(1);
;     for (int kt = 0; kt < nk; ++kt) {
;       if (kt + 1 < nk) {
;         if (MF == 8) asm volatile("s_waitcnt vmcnt(6)" ::: "memory");
;         else asm volatile("s_waitcnt vmcnt(3)" ::: "memory");
;       } else asm volatile("s_waitcnt vmcnt(0)" ::: "memory");
;       asm volatile("s_waitcnt lgkmcnt(0)" ::: "memory");
;       __builtin_amdgcn_s_barrier();
;       const u16* a_ = sbase + (kt % 3) * STG;
;       const u16* b_ = a_ + BM * 32;
;       bf16x8 bfr[4], afc[2], afn[2];
;       const u16* ap_ = a_ + (wr * (16 * MF) + fr) * 32 + fq * 8;
; #pragma unroll
;       for (int n = 0; n < 4; ++n) bfr[n] = rd_std(b_ + (wc * 64 + n * 16 + fr) * 32 + fq * 8);
;       afc[0] = rd_std(ap_); afc[1] = rd_std(ap_ + 16 * 32);
;       __builtin_amdgcn_sched_barrier(0);
;       if (kt + 2 < nk) GEMM_ISSUE(kt + 2);
;       __builtin_amdgcn_sched_barrier(0);
; #pragma unroll
;       for (int mh = 0; mh < MF / 2; ++mh) {
;         if (mh + 1 < MF / 2) {
;           afn[0] = rd_std(ap_ + ((mh + 1) * 2) * 16 * 32);
;           afn[1] = rd_std(ap_ + ((mh + 1) * 2 + 1) * 16 * 32);
;         }
;         __builtin_amdgcn_sched_barrier(0);
; #pragma unroll
;         for (int m = 0; m < 2; ++m)
; #pragma unroll
;           for (int n = 0; n < 4; ++n) acc[mh * 2 + m][n] = MFMA(bfr[n], afc[m], acc[mh * 2 + m][n]);
;         __builtin_amdgcn_sched_barrier(0);
;         afc[0] = afn[0]; afc[1] = afn[1];
;       }
.LBB0_338:
	s_mul_hi_u32 s17, s15, 0xaaaaaaab
	s_lshr_b32 s17, s17, 1
	s_mul_i32 s17, s17, 0x9000
	s_mul_hi_u32 s16, s11, 0xaaaaaaab
	v_subrev_u32_e32 v44, s17, v60
	v_add_u32_e32 v97, s3, v58
	s_lshr_b32 s16, s16, 1
	s_waitcnt vmcnt(3)
	v_add_u32_e32 v74, v97, v44
	s_mul_i32 s16, s16, 0x9000
	v_subrev_u32_e32 v78, s17, v61
	s_waitcnt lgkmcnt(0)
	s_barrier
	ds_read_b128 v[44:47], v74 offset:4096
	ds_read_b128 v[48:51], v74 offset:5120
	ds_read_b128 v[70:73], v74 offset:6144
	ds_read_b128 v[74:77], v74 offset:7168
	v_subrev_u32_e32 v92, s16, v60
	v_subrev_u32_e32 v93, s16, v62
	s_mul_hi_u32 s16, s10, 0xaaaaaaab
	v_add_u32_e32 v82, v97, v78
	s_lshr_b32 s16, s16, 1
	ds_read_b128 v[78:81], v82
	ds_read_b128 v[82:85], v82 offset:1024
	s_mul_i32 s16, s16, 0x9000
	v_subrev_u32_e32 v94, s16, v63
	v_subrev_u32_e32 v95, s16, v64
	v_subrev_u32_e32 v96, s16, v65
	s_mul_hi_u32 s16, s14, 0xaaaaaaab
	s_lshr_b32 s16, s16, 1
	s_mul_i32 s16, s16, 0x9000
	s_nop 0
	v_subrev_u32_e32 v90, s16, v66
	v_subrev_u32_e32 v98, s16, v67
	v_subrev_u32_e32 v99, s16, v68
	s_add_i32 s16, s3, 0
	v_add_u32_e32 v90, s16, v90
	v_lshl_add_u64 v[86:87], v[42:43], 0, v[38:39]
	v_readfirstlane_b32 s17, v90
	v_lshl_add_u64 v[88:89], v[86:87], 0, s[74:75]
	s_mov_b32 m0, s17
	v_add_u32_e32 v98, s16, v98
	global_load_lds_dwordx4 v[88:89], off
	v_lshl_add_u64 v[88:89], v[40:41], 0, v[38:39]
	v_readfirstlane_b32 s17, v98
	v_add_u32_e32 v98, s16, v99
	v_lshl_add_u64 v[90:91], v[88:89], 0, s[74:75]
	s_mov_b32 m0, s17
	v_readfirstlane_b32 s17, v98
	global_load_lds_dwordx4 v[90:91], off
	v_lshl_add_u64 v[90:91], v[88:89], 0, s[56:57]
	s_mov_b32 m0, s17
	s_add_i32 s15, s15, 2
	global_load_lds_dwordx4 v[90:91], off
	s_waitcnt lgkmcnt(0)
	v_mfma_f32_16x16x32_bf16 v[30:33], v[44:47], v[78:81], v[30:33]
	v_mfma_f32_16x16x32_bf16 v[26:29], v[48:51], v[78:81], v[26:29]
	v_mfma_f32_16x16x32_bf16 v[22:25], v[70:73], v[78:81], v[22:25]
	v_mfma_f32_16x16x32_bf16 v[18:21], v[74:77], v[78:81], v[18:21]
	v_mfma_f32_16x16x32_bf16 v[14:17], v[44:47], v[82:85], v[14:17]
	v_mfma_f32_16x16x32_bf16 v[10:13], v[48:51], v[82:85], v[10:13]
	v_mfma_f32_16x16x32_bf16 v[6:9], v[70:73], v[82:85], v[6:9]
	v_mfma_f32_16x16x32_bf16 v[2:5], v[74:77], v[82:85], v[2:5]
	s_waitcnt vmcnt(3)
	v_add_u32_e32 v74, v97, v92
	s_waitcnt lgkmcnt(0)
	s_barrier
	ds_read_b128 v[44:47], v74 offset:16384
	ds_read_b128 v[48:51], v74 offset:17408
	ds_read_b128 v[70:73], v74 offset:18432
	ds_read_b128 v[74:77], v74 offset:19456
	v_add_u32_e32 v82, v97, v93
	ds_read_b128 v[78:81], v82
	ds_read_b128 v[82:85], v82 offset:1024
	v_add_u32_e32 v90, s16, v96
	v_lshl_add_u64 v[86:87], v[86:87], 0, s[52:53]
	v_lshl_add_u64 v[86:87], v[86:87], 0, 64
	v_readfirstlane_b32 s17, v90
	v_add_u32_e32 v90, s16, v95
	s_mov_b32 m0, s17
	v_readfirstlane_b32 s17, v90
	global_load_lds_dwordx4 v[86:87], off
	v_lshl_add_u64 v[86:87], v[88:89], 0, s[52:53]
	v_lshl_add_u64 v[86:87], v[86:87], 0, 64
	s_mov_b32 m0, s17
	s_nop 0
	global_load_lds_dwordx4 v[86:87], off
	v_lshl_add_u64 v[86:87], v[88:89], 0, s[0:1]
	v_lshl_add_u64 v[86:87], v[86:87], 0, 64
	v_add_u32_e32 v88, s16, v94
	s_nop 0
	v_readfirstlane_b32 s16, v88
	s_mov_b32 m0, s16
	s_nop 0
	global_load_lds_dwordx4 v[86:87], off
	s_waitcnt lgkmcnt(0)
	v_mfma_f32_16x16x32_bf16 v[30:33], v[44:47], v[78:81], v[30:33]
	v_mfma_f32_16x16x32_bf16 v[26:29], v[48:51], v[78:81], v[26:29]
	v_mfma_f32_16x16x32_bf16 v[22:25], v[70:73], v[78:81], v[22:25]
	v_mfma_f32_16x16x32_bf16 v[18:21], v[74:77], v[78:81], v[18:21]
	v_mfma_f32_16x16x32_bf16 v[14:17], v[44:47], v[82:85], v[14:17]
	v_mfma_f32_16x16x32_bf16 v[10:13], v[48:51], v[82:85], v[10:13]
	v_mfma_f32_16x16x32_bf16 v[6:9], v[70:73], v[82:85], v[6:9]
	v_mfma_f32_16x16x32_bf16 v[2:5], v[74:77], v[82:85], v[2:5]
	s_addk_i32 s3, 0x6000
	s_add_i32 s11, s11, 2
	s_add_i32 s10, s10, 2
	s_add_i32 s14, s14, 2
	v_lshl_add_u64 v[40:41], v[40:41], 0, s[74:75]
	v_lshl_add_u64 v[40:41], v[40:41], 0, s[74:75]
	s_cmp_eq_u32 s3, 0x102000
	v_lshl_add_u64 v[42:43], v[42:43], 0, s[74:75]
	v_lshl_add_u64 v[42:43], v[42:43], 0, s[74:75]
	s_cbranch_scc0 .LBB0_338
; #define MFMA(a, b, c) __builtin_amdgcn_mfma_f32_16x16x32_bf16((a), (b), (c), 0, 0, 0)
; template <int EPI, int MF>
; __device__ __forceinline__ void gemm_part(const u16* __restrict__ A, int lda, const u16* __restrict__ Bt, int K, int ntn, GemmEpi ep, char* smem,
;                                           int mbase, int mrows) {
;     ...
; #pragma unroll
;       for (int n = 0; n < 4; ++n) bfr[n] = rd_std(b_ + (wc * 64 + n * 16 + fr) * 32 + fq * 8);
;       afc[0] = rd_std(ap_); afc[1] = rd_std(ap_ + 16 * 32);
;       __builtin_amdgcn_sched_barrier(0);
;       if (kt + 2 < nk) GEMM_ISSUE(kt + 2);
;       __builtin_amdgcn_sched_barrier(0);
; #pragma unroll
;       for (int mh = 0; mh < MF / 2; ++mh) {
;         if (mh + 1 < MF / 2) {
;           afn[0] = rd_std(ap_ + ((mh + 1) * 2) * 16 * 32);
;           afn[1] = rd_std(ap_ + ((mh + 1) * 2 + 1) * 16 * 32);
;         }
;         __builtin_amdgcn_sched_barrier(0);
; #pragma unroll
;         for (int m = 0; m < 2; ++m)
; #pragma unroll
;           for (int n = 0; n < 4; ++n) acc[mh * 2 + m][n] = MFMA(bfr[n], afc[m], acc[mh * 2 + m][n]);
;         __builtin_amdgcn_sched_barrier(0);
;         afc[0] = afn[0]; afc[1] = afn[1];
;       }
;     ...
;       } else if (EPI == EPI_RESID) {
;         const float* rp = (row < MP) ? ep.res0 + (size_t)row * DM : ep.res1 + (size_t)(row - MP) * DM;
;         float ssq = 0.f;
; #pragma unroll
;         for (int n = 0; n < 4; ++n) {
;           const int col = cb + n * 16;
;           const float4 r = *(const float4*)(rp + col);
;           float4 v;
;           v.x = r.x + ep.scale * acc[m][n][0]; v.y = r.y + ep.scale * acc[m][n][1];
;           v.z = r.z + ep.scale * acc[m][n][2]; v.w = r.w + ep.scale * acc[m][n][3];
;           *(float4*)(ep.outf + (size_t)row * DM + col) = v;
;           if (ep.xcopy) {
;             bf16x4 o;
;             o[0] = (short)f2bf(v.x); o[1] = (short)f2bf(v.y); o[2] = (short)f2bf(v.z); o[3] = (short)f2bf(v.w);
;             *(bf16x4*)(ep.xcopy + (size_t)row * DM + col) = o;
	s_waitcnt vmcnt(3)
	s_waitcnt lgkmcnt(0)
	s_barrier
	ds_read_b128 v[40:43], v69 offset:28672
	ds_read_b128 v[44:47], v69 offset:29696
	ds_read_b128 v[48:51], v69 offset:30720
	ds_read_b128 v[70:73], v69 offset:31744
	ds_read_b128 v[74:77], v59 offset:24576
	ds_read_b128 v[78:81], v59 offset:25600
	s_mul_hi_u32 s10, s11, 0xaaaaaaab
	s_lshr_b32 s10, s10, 1
	s_mul_i32 s10, s10, 0x9000
	s_sub_i32 s3, s3, s10
	s_add_i32 s3, s3, 0
	s_addk_i32 s3, 0x3000
	s_waitcnt lgkmcnt(0)
	v_mfma_f32_16x16x32_bf16 v[30:33], v[40:43], v[74:77], v[30:33]
	v_mfma_f32_16x16x32_bf16 v[26:29], v[44:47], v[74:77], v[26:29]
	v_mfma_f32_16x16x32_bf16 v[22:25], v[48:51], v[74:77], v[22:25]
	v_mfma_f32_16x16x32_bf16 v[18:21], v[70:73], v[74:77], v[18:21]
	v_mfma_f32_16x16x32_bf16 v[14:17], v[40:43], v[78:81], v[14:17]
	v_mfma_f32_16x16x32_bf16 v[10:13], v[44:47], v[78:81], v[10:13]
	v_mfma_f32_16x16x32_bf16 v[6:9], v[48:51], v[78:81], v[6:9]
	v_mfma_f32_16x16x32_bf16 v[2:5], v[70:73], v[78:81], v[2:5]
	v_lshl_add_u32 v40, v54, 1, s3
	s_waitcnt vmcnt(0)
	v_add3_u32 v70, v40, v57, v53
	s_waitcnt lgkmcnt(0)
	s_barrier
	ds_read_b128 v[40:43], v70 offset:4096
	ds_read_b128 v[44:47], v70 offset:5120
	ds_read_b128 v[48:51], v70 offset:6144
	ds_read_b128 v[70:73], v70 offset:7168
	ds_read_b128 v[74:77], v59
	ds_read_b128 v[78:81], v59 offset:1024
	s_waitcnt lgkmcnt(0)
	v_mfma_f32_16x16x32_bf16 v[30:33], v[40:43], v[74:77], v[30:33]
	v_mfma_f32_16x16x32_bf16 v[26:29], v[44:47], v[74:77], v[26:29]
	v_mfma_f32_16x16x32_bf16 v[22:25], v[48:51], v[74:77], v[22:25]
	v_mfma_f32_16x16x32_bf16 v[18:21], v[70:73], v[74:77], v[18:21]
	v_mfma_f32_16x16x32_bf16 v[14:17], v[40:43], v[78:81], v[14:17]
	v_mfma_f32_16x16x32_bf16 v[10:13], v[44:47], v[78:81], v[10:13]
	v_mfma_f32_16x16x32_bf16 v[6:9], v[48:51], v[78:81], v[6:9]
	v_mfma_f32_16x16x32_bf16 v[2:5], v[70:73], v[78:81], v[2:5]
	v_add_u32_e32 v42, s2, v55
	s_waitcnt vmcnt(0)
	s_barrier
	s_mov_b32 s2, 0xffff
	v_cmp_lt_i32_e32 vcc, s2, v42
	s_and_saveexec_b64 s[2:3], vcc
	s_xor_b64 s[2:3], exec, s[2:3]
	v_add_u32_e32 v40, 0xffff0000, v42
	v_mov_b32_e32 v41, v0
	v_lshlrev_b64 v[40:41], 12, v[40:41]
	v_lshl_add_u64 v[46:47], s[18:19], 0, v[40:41]
	v_mov_b32_e32 v43, v0
	s_andn2_saveexec_b64 s[2:3], s[2:3]
	v_ashrrev_i32_e32 v43, 31, v42
	v_lshlrev_b64 v[40:41], 12, v[42:43]
	v_lshl_add_u64 v[46:47], s[8:9], 0, v[40:41]
	s_or_b64 exec, exec, s[2:3]
	v_or_b32_e32 v40, s5, v56
	v_lshlrev_b64 v[44:45], 12, v[42:43]
	v_lshl_add_u64 v[50:51], s[26:27], 0, v[44:45]
	v_lshlrev_b64 v[44:45], 11, v[42:43]
	v_ashrrev_i32_e32 v41, 31, v40
	v_lshl_add_u64 v[74:75], s[44:45], 0, v[44:45]
	v_lshlrev_b64 v[44:45], 2, v[40:41]
	v_lshl_add_u64 v[48:49], v[46:47], 0, v[44:45]
	global_load_dwordx4 v[70:73], v[48:49], off
	v_readlane_b32 s2, v253, 24
	v_readlane_b32 s3, v253, 25
	v_lshl_add_u64 v[46:47], v[50:51], 0, v[44:45]
	s_andn2_b64 vcc, exec, s[2:3]
	v_cndmask_b32_e64 v50, 0, 1, s[2:3]
	v_cmp_ne_u32_e64 s[14:15], 1, v50
	v_lshl_add_u64 v[50:51], v[40:41], 1, v[74:75]
	s_waitcnt vmcnt(0)
	v_pk_fma_f32 v[30:31], v[30:31], 0.5, v[70:71] op_sel_hi:[1,0,1]
	v_pk_fma_f32 v[32:33], v[32:33], 0.5, v[72:73] op_sel_hi:[1,0,1]
	global_store_dwordx4 v[46:47], v[30:33], off
	s_cbranch_vccnz .LBB0_345
	v_cvt_pk_bf16_f32 v70, v30, v31
	v_cvt_pk_bf16_f32 v71, v32, v33
	v_lshlrev_b32_e32 v84, 1, v50
	v_bfi_b32 v84, s100, v84, v50
	v_lshrrev_b32_e32 v85, 5, v50
	v_bfi_b32 v84, 64, v85, v84
	v_mov_b32_e32 v85, v51
	global_store_dwordx2 v[84:85], v[70:71], off
